# out-projection K-loops: A tile loads issued a full iteration ahead (two staging sets), W addresses formed in destination registers
# speedup vs baseline: 1.0219x; 1.0004x over previous
; #define A256_LOADH(kt_, hf_) { a0 = la.ld1(kt_, (hf_) * 4 + 0, tid); a1 = la.ld1(kt_, (hf_) * 4 + 1, tid); a2 = la.ld1(kt_, (hf_) * 4 + 2, tid); a3 = la.ld1(kt_, (hf_) * 4 + 3, tid); }
; #define ZERO_ACC8(a) { _Pragma("unroll") for (int i_ = 0; i_ < 8; i_++) _Pragma("unroll") for (int r_ = 0; r_ < 16; r_++) a[i_][r_] = 0.f; }
; template <bool swap, class LA>
; DI void gemm256_ws(const LA& la, const bf16_t* Wt, const int KS, const int nk, bf16_t* smem, f32x16 (&acc)[8]) {
;     ...
;   A256_LOADH(0, 0) A256_STH(smem, 0)
;   A256_LOADH(0, 1) A256_STH(smem, 1)
;   W256_LD(0, 0, w00, w10) W256_LD(0, 1, w01, w11) W256_LD(0, 2, w02, w12) W256_LD(0, 3, w03, w13)
;   __syncthreads();
;   const int aoff = (tbk * 128 + l32) * LDT + h * 8;
; DI void ph_out(const Params& P, int layer, bf16_t* smem) {
;     ...
;   for (int it = 0;; it++) {
;     int mt, nt; if (!tile_sched256(bid, it, 8, 8, mt, nt)) break;
;     const int m0 = mt * 256, n0 = nt * 128;
;     __syncthreads();
;     f32x16 acc[8]; ZERO_ACC8(acc)
;     LoadTile256 la{cat + (size_t)(2 * mt) * 16 * 8192, 16 * 8192};
;     gemm256_ws<true>(la, W + (size_t)n0 * 1024, 64, 16, smem, acc);
.LBB0_29:
	s_ashr_i32 s3, s2, 31
	s_lshr_b32 s3, s3, 24
	s_add_i32 s3, s2, s3
	s_ashr_i32 s6, s3, 8
	s_and_b32 s3, s3, 0xffffff00
	s_sub_i32 s2, s2, s3
	s_ashr_i32 s3, s2, 31
	s_lshr_b32 s3, s3, 29
	s_add_i32 s3, s2, s3
	s_ashr_i32 s17, s3, 3
	s_sub_i32 s3, s6, s17
	s_add_i32 s17, s17, s14
	s_lshl_b32 s16, s3, 3
	s_lshl_b32 s6, s17, 1
	s_add_i32 s16, s16, s2
	s_ashr_i32 s7, s6, 31
	s_lshl_b32 s2, s16, 7
	s_lshl_b64 s[6:7], s[6:7], 18
	v_mov_b32_e32 v0, v234
	s_barrier
	s_add_u32 s8, s84, s6
	s_addc_u32 s9, s85, s7
	v_lshlrev_b32_e32 v2, 3, v0
	s_ashr_i32 s3, s2, 31
	v_add_u32_e32 v6, 0x800, v2
	s_lshl_b64 s[6:7], s[2:3], 11
	v_readlane_b32 s10, v255, 25
	v_ashrrev_i32_e32 v3, 31, v2
	v_ashrrev_i32_e32 v7, 31, v6
	v_readlane_b32 s11, v255, 26
	s_add_u32 s6, s10, s6
	v_lshlrev_b64 v[176:177], 1, v[2:3]
	v_lshlrev_b64 v[178:179], 1, v[6:7]
	v_add_u32_e32 v6, 0x1000, v2
	v_add_u32_e32 v2, 0x1800, v2
	s_addc_u32 s7, s11, s7
	v_ashrrev_i32_e32 v7, 31, v6
	v_ashrrev_i32_e32 v3, 31, v2
	v_lshlrev_b64 v[180:181], 1, v[6:7]
	v_lshlrev_b64 v[182:183], 1, v[2:3]
	s_add_u32 s10, s8, 0x40000
	v_lshl_add_u64 v[4:5], s[8:9], 0, v[176:177]
	v_lshl_add_u64 v[8:9], s[8:9], 0, v[178:179]
	v_lshl_add_u64 v[12:13], s[8:9], 0, v[180:181]
	v_lshl_add_u64 v[2:3], s[8:9], 0, v[182:183]
	s_addc_u32 s11, s9, 0
	v_ashrrev_i32_e32 v36, 6, v0
	global_load_dwordx4 v[4:7], v[4:5], off
	s_nop 0
	global_load_dwordx4 v[8:11], v[8:9], off
	s_nop 0
	global_load_dwordx4 v[12:15], v[12:13], off
	s_nop 0
	global_load_dwordx4 v[16:19], v[2:3], off
	v_lshl_add_u64 v[2:3], s[10:11], 0, v[176:177]
	v_lshl_add_u64 v[24:25], s[10:11], 0, v[178:179]
	v_lshl_add_u64 v[28:29], s[10:11], 0, v[180:181]
	v_lshl_add_u64 v[32:33], s[10:11], 0, v[182:183]
	v_lshlrev_b32_e32 v37, 4, v0
	v_and_b32_e32 v36, -2, v36
	global_load_dwordx4 v[20:23], v[2:3], off
	s_nop 0
	global_load_dwordx4 v[24:27], v[24:25], off
	s_nop 0
	global_load_dwordx4 v[28:31], v[28:29], off
	s_nop 0
	global_load_dwordx4 v[32:35], v[32:33], off
	v_and_b32_e32 v3, 31, v0
	v_lshrrev_b32_e32 v39, 3, v0
	v_lshlrev_b32_e32 v40, 1, v0
	v_lshrrev_b32_e32 v41, 1, v0
	v_and_b32_e32 v0, 0x3f0, v37
	v_and_b32_e32 v38, 0x70, v37
	v_ashrrev_i32_e32 v37, 31, v36
	v_lshlrev_b64 v[36:37], 16, v[36:37]
	v_lshl_add_u64 v[36:37], s[6:7], 0, v[36:37]
	v_lshl_add_u64 v[186:187], v[36:37], 0, v[0:1]
	s_mov_b64 s[6:7], 0x10000
	v_lshl_add_u64 v[188:189], v[186:187], 0, s[6:7]
	v_add_co_u32_e64 v36, s[6:7], s94, v186
	s_movk_i32 s18, 0x80
	s_nop 0
	v_addc_co_u32_e64 v37, s[6:7], 0, v187, s[6:7]
	global_load_dwordx4 v[154:157], v[36:37], off
	global_load_dwordx4 v[158:161], v[186:187], off
	global_load_dwordx4 v[146:149], v[36:37], off offset:1024
	global_load_dwordx4 v[150:153], v[186:187], off offset:1024
	global_load_dwordx4 v[142:145], v[36:37], off offset:2048
	global_load_dwordx4 v[138:141], v[186:187], off offset:2048
	global_load_dwordx4 v[130:133], v[36:37], off offset:3072
	global_load_dwordx4 v[134:137], v[186:187], off offset:3072
	v_mov_b32_e32 v2, 0
	v_and_or_b32 v3, v40, s18, v3
	v_and_b32_e32 v40, 16, v41
	v_mad_u64_u32 v[184:185], s[18:19], v39, s0, v[38:39]
	v_mad_u32_u24 v169, v3, s0, v40
	s_mov_b32 s6, 0
	v_mov_b32_e32 v3, v2
	v_mov_b32_e32 v50, v2
	v_mov_b32_e32 v51, v2
	v_mov_b32_e32 v52, v2
	v_mov_b32_e32 v53, v2
	v_mov_b32_e32 v54, v2
	v_mov_b32_e32 v55, v2
	v_mov_b32_e32 v56, v2
	v_mov_b32_e32 v57, v2
	v_mov_b32_e32 v58, v2
	v_mov_b32_e32 v59, v2
	v_mov_b32_e32 v60, v2
	v_mov_b32_e32 v61, v2
	v_mov_b32_e32 v62, v2
	v_mov_b32_e32 v63, v2
	v_mov_b32_e32 v64, v2
	v_mov_b32_e32 v65, v2
	v_mov_b32_e32 v82, v2
	s_waitcnt vmcnt(15)
	ds_write_b128 v184, v[4:7]
	s_waitcnt vmcnt(14)
	ds_write_b128 v184, v[8:11] offset:4608
	s_waitcnt vmcnt(13)
	ds_write_b128 v184, v[12:15] offset:9216
	s_waitcnt vmcnt(12)
	ds_write_b128 v184, v[16:19] offset:13824
	s_waitcnt vmcnt(11)
	ds_write_b128 v184, v[20:23] offset:18432
	s_waitcnt vmcnt(10)
	ds_write_b128 v184, v[24:27] offset:23040
	s_waitcnt vmcnt(9)
	ds_write_b128 v184, v[28:31] offset:27648
	s_waitcnt vmcnt(8)
	ds_write_b128 v184, v[32:35] offset:32256
	v_mov_b32_e32 v4, v2
	v_mov_b32_e32 v5, v2
	v_mov_b32_e32 v6, v2
	v_mov_b32_e32 v7, v2
	v_mov_b32_e32 v8, v2
	v_mov_b32_e32 v9, v2
	v_mov_b32_e32 v10, v2
	v_mov_b32_e32 v11, v2
	v_mov_b32_e32 v12, v2
	v_mov_b32_e32 v13, v2
	v_mov_b32_e32 v14, v2
	v_mov_b32_e32 v15, v2
	v_mov_b32_e32 v16, v2
	v_mov_b32_e32 v17, v2
	v_mov_b32_e32 v18, v2
	v_mov_b32_e32 v19, v2
	v_mov_b32_e32 v20, v2
	v_mov_b32_e32 v21, v2
	v_mov_b32_e32 v22, v2
	v_mov_b32_e32 v23, v2
	v_mov_b32_e32 v24, v2
	v_mov_b32_e32 v25, v2
	v_mov_b32_e32 v26, v2
	v_mov_b32_e32 v27, v2
	v_mov_b32_e32 v28, v2
	v_mov_b32_e32 v29, v2
	v_mov_b32_e32 v30, v2
	v_mov_b32_e32 v31, v2
	v_mov_b32_e32 v32, v2
	v_mov_b32_e32 v33, v2
	v_mov_b32_e32 v83, v2
	v_mov_b32_e32 v84, v2
	v_mov_b32_e32 v85, v2
	v_mov_b32_e32 v86, v2
	v_mov_b32_e32 v87, v2
	v_mov_b32_e32 v88, v2
	v_mov_b32_e32 v89, v2
	v_mov_b32_e32 v90, v2
	v_mov_b32_e32 v91, v2
	v_mov_b32_e32 v92, v2
	v_mov_b32_e32 v93, v2
	v_mov_b32_e32 v94, v2
	v_mov_b32_e32 v95, v2
	v_mov_b32_e32 v96, v2
	v_mov_b32_e32 v97, v2
	v_mov_b32_e32 v34, v2
	v_mov_b32_e32 v35, v2
	v_mov_b32_e32 v36, v2
	v_mov_b32_e32 v37, v2
	v_mov_b32_e32 v38, v2
	v_mov_b32_e32 v39, v2
	v_mov_b32_e32 v40, v2
	v_mov_b32_e32 v41, v2
	v_mov_b32_e32 v42, v2
	v_mov_b32_e32 v43, v2
	v_mov_b32_e32 v44, v2
	v_mov_b32_e32 v45, v2
	v_mov_b32_e32 v46, v2
	v_mov_b32_e32 v47, v2
	v_mov_b32_e32 v48, v2
	v_mov_b32_e32 v49, v2
	v_mov_b32_e32 v66, v2
	v_mov_b32_e32 v67, v2
	v_mov_b32_e32 v68, v2
	v_mov_b32_e32 v69, v2
	v_mov_b32_e32 v70, v2
	v_mov_b32_e32 v71, v2
	v_mov_b32_e32 v72, v2
	v_mov_b32_e32 v73, v2
	v_mov_b32_e32 v74, v2
	v_mov_b32_e32 v75, v2
	v_mov_b32_e32 v76, v2
	v_mov_b32_e32 v77, v2
	v_mov_b32_e32 v78, v2
	v_mov_b32_e32 v79, v2
	v_mov_b32_e32 v80, v2
	v_mov_b32_e32 v81, v2
	v_mov_b32_e32 v98, v2
	v_mov_b32_e32 v99, v2
	v_mov_b32_e32 v100, v2
	v_mov_b32_e32 v101, v2
	v_mov_b32_e32 v102, v2
	v_mov_b32_e32 v103, v2
	v_mov_b32_e32 v104, v2
	v_mov_b32_e32 v105, v2
	v_mov_b32_e32 v106, v2
	v_mov_b32_e32 v107, v2
	v_mov_b32_e32 v108, v2
	v_mov_b32_e32 v109, v2
	v_mov_b32_e32 v110, v2
	v_mov_b32_e32 v111, v2
	v_mov_b32_e32 v112, v2
	v_mov_b32_e32 v113, v2
	v_mov_b32_e32 v114, v2
	v_mov_b32_e32 v115, v2
	v_mov_b32_e32 v116, v2
	v_mov_b32_e32 v117, v2
	v_mov_b32_e32 v118, v2
	v_mov_b32_e32 v119, v2
	v_mov_b32_e32 v120, v2
	v_mov_b32_e32 v121, v2
	v_mov_b32_e32 v122, v2
	v_mov_b32_e32 v123, v2
	v_mov_b32_e32 v124, v2
	v_mov_b32_e32 v125, v2
	v_mov_b32_e32 v126, v2
	v_mov_b32_e32 v127, v2
	v_mov_b32_e32 v128, v2
	v_mov_b32_e32 v129, v2
	s_waitcnt lgkmcnt(0)
	s_barrier
; #define A256_LOADH(kt_, hf_) { a0 = la.ld1(kt_, (hf_) * 4 + 0, tid); a1 = la.ld1(kt_, (hf_) * 4 + 1, tid); a2 = la.ld1(kt_, (hf_) * 4 + 2, tid); a3 = la.ld1(kt_, (hf_) * 4 + 3, tid); }
; template <bool swap, class LA>
; DI void gemm256_ws(const LA& la, const bf16_t* Wt, const int KS, const int nk, bf16_t* smem, f32x16 (&acc)[8]) {
;     ...
;   for (int kt = 0; kt < nk; kt++) {
;     const int cur = kt & 1; const int kn = (kt + 1 < nk) ? kt + 1 : last;
;     const bf16_t* sp = smem + cur * ATILE_E + aoff;
;     bf16_t* nxt = smem + (cur ^ 1) * ATILE_E;
;     A256_LOADH(kn, 0)
;     MMA256(0, w00, w10) W256_LD(kn, 0, w00, w10)
;     MMA256(1, w01, w11) W256_LD(kn, 1, w01, w11)
;     A256_STH(nxt, 0)
;     A256_LOADH(kn, 1)
;     MMA256(2, w02, w12) W256_LD(kn, 2, w02, w12)
;     MMA256(3, w03, w13) W256_LD(kn, 3, w03, w13)
;     A256_STH(nxt, 1)
;     __syncthreads();
	s_lshl_b32 s36, 1, 14
	s_add_u32 s18, s8, s36
	s_addc_u32 s19, s9, 0
	v_lshl_add_u64 v[206:207], s[18:19], 0, v[176:177]
	v_lshl_add_u64 v[210:211], s[18:19], 0, v[178:179]
	v_lshl_add_u64 v[214:215], s[18:19], 0, v[180:181]
	v_lshl_add_u64 v[218:219], s[18:19], 0, v[182:183]
	global_load_dwordx4 v[206:209], v[206:207], off
	global_load_dwordx4 v[210:213], v[210:211], off
	global_load_dwordx4 v[214:217], v[214:215], off
	global_load_dwordx4 v[218:221], v[218:219], off
	s_add_u32 s18, s10, s36
	s_addc_u32 s19, s11, 0
	v_lshl_add_u64 v[222:223], s[18:19], 0, v[176:177]
	v_lshl_add_u64 v[226:227], s[18:19], 0, v[178:179]
	v_lshl_add_u64 v[230:231], s[18:19], 0, v[180:181]
	v_lshl_add_u64 v[246:247], s[18:19], 0, v[182:183]
	global_load_dwordx4 v[222:225], v[222:223], off
	global_load_dwordx4 v[226:229], v[226:227], off
	global_load_dwordx4 v[230:233], v[230:231], off
	global_load_dwordx4 v[246:249], v[246:247], off
.LBB0_30:
	s_and_b32 s7, s6, 1
	s_mul_i32 s18, s7, 0x9000
	v_add_u32_e32 v0, s18, v169
	ds_read_b128 v[190:193], v0
	ds_read_b128 v[194:197], v0 offset:4608
	ds_read_b128 v[198:201], v0 offset:9216
	ds_read_b128 v[202:205], v0 offset:13824
	s_add_i32 s6, s6, 1
	s_min_u32 s29, s6, 15
	s_xor_b32 s7, s7, 1
	s_mul_i32 s7, s7, 0x9000
	v_add_u32_e32 v171, s7, v184
	s_lshl_b32 s90, s29, 12
	s_add_i32 s29, s6, 1
	s_min_u32 s29, s29, 15
	s_lshl_b32 s36, s29, 14
	s_waitcnt vmcnt(14) lgkmcnt(3)
	v_mfma_f32_32x32x16_bf16 v[82:97], v[154:157], v[190:193], v[82:97]
	v_mfma_f32_32x32x16_bf16 v[114:129], v[158:161], v[190:193], v[114:129]
	ds_read_b128 v[190:193], v0 offset:32
	s_waitcnt lgkmcnt(3)
	v_mfma_f32_32x32x16_bf16 v[50:65], v[154:157], v[194:197], v[50:65]
	v_mfma_f32_32x32x16_bf16 v[98:113], v[158:161], v[194:197], v[98:113]
	ds_read_b128 v[194:197], v0 offset:4640
	s_waitcnt lgkmcnt(3)
	v_mfma_f32_32x32x16_bf16 v[18:33], v[154:157], v[198:201], v[18:33]
	v_mfma_f32_32x32x16_bf16 v[66:81], v[158:161], v[198:201], v[66:81]
	ds_read_b128 v[198:201], v0 offset:9248
	s_waitcnt lgkmcnt(3)
	v_mfma_f32_32x32x16_bf16 v[2:17], v[154:157], v[202:205], v[2:17]
	v_mfma_f32_32x32x16_bf16 v[34:49], v[158:161], v[202:205], v[34:49]
	ds_read_b128 v[202:205], v0 offset:13856
	v_lshl_add_u64 v[154:155], v[188:189], 0, s[90:91]
	global_load_dwordx4 v[154:157], v[154:155], off
	v_lshl_add_u64 v[158:159], v[186:187], 0, s[90:91]
	global_load_dwordx4 v[158:161], v[158:159], off
	s_waitcnt vmcnt(14) lgkmcnt(3)
	v_mfma_f32_32x32x16_bf16 v[82:97], v[146:149], v[190:193], v[82:97]
	v_mfma_f32_32x32x16_bf16 v[114:129], v[150:153], v[190:193], v[114:129]
	ds_read_b128 v[190:193], v0 offset:64
	s_waitcnt lgkmcnt(3)
	v_mfma_f32_32x32x16_bf16 v[50:65], v[146:149], v[194:197], v[50:65]
	v_mfma_f32_32x32x16_bf16 v[98:113], v[150:153], v[194:197], v[98:113]
	ds_read_b128 v[194:197], v0 offset:4672
	s_waitcnt lgkmcnt(3)
	v_mfma_f32_32x32x16_bf16 v[18:33], v[146:149], v[198:201], v[18:33]
	v_mfma_f32_32x32x16_bf16 v[66:81], v[150:153], v[198:201], v[66:81]
	ds_read_b128 v[198:201], v0 offset:9280
	s_waitcnt lgkmcnt(3)
	v_mfma_f32_32x32x16_bf16 v[2:17], v[146:149], v[202:205], v[2:17]
	v_mfma_f32_32x32x16_bf16 v[34:49], v[150:153], v[202:205], v[34:49]
	ds_read_b128 v[202:205], v0 offset:13888
	v_lshl_add_u64 v[146:147], v[188:189], 0, s[90:91]
	global_load_dwordx4 v[146:149], v[146:147], off offset:1024
	v_lshl_add_u64 v[150:151], v[186:187], 0, s[90:91]
	global_load_dwordx4 v[150:153], v[150:151], off offset:1024
	s_waitcnt vmcnt(8)
	ds_write_b128 v171, v[206:209]
	ds_write_b128 v171, v[210:213] offset:4608
	ds_write_b128 v171, v[214:217] offset:9216
	ds_write_b128 v171, v[218:221] offset:13824
	s_add_u32 s18, s8, s36
	s_addc_u32 s19, s9, 0
	v_lshl_add_u64 v[206:207], s[18:19], 0, v[176:177]
	v_lshl_add_u64 v[210:211], s[18:19], 0, v[178:179]
	v_lshl_add_u64 v[214:215], s[18:19], 0, v[180:181]
	v_lshl_add_u64 v[218:219], s[18:19], 0, v[182:183]
	global_load_dwordx4 v[206:209], v[206:207], off
	global_load_dwordx4 v[210:213], v[210:211], off
	global_load_dwordx4 v[214:217], v[214:215], off
	global_load_dwordx4 v[218:221], v[218:219], off
	s_waitcnt lgkmcnt(7)
	v_mfma_f32_32x32x16_bf16 v[82:97], v[142:145], v[190:193], v[82:97]
	v_mfma_f32_32x32x16_bf16 v[114:129], v[138:141], v[190:193], v[114:129]
	ds_read_b128 v[190:193], v0 offset:96
	s_waitcnt lgkmcnt(7)
	v_mfma_f32_32x32x16_bf16 v[50:65], v[142:145], v[194:197], v[50:65]
	v_mfma_f32_32x32x16_bf16 v[98:113], v[138:141], v[194:197], v[98:113]
	ds_read_b128 v[194:197], v0 offset:4704
	s_waitcnt lgkmcnt(7)
	v_mfma_f32_32x32x16_bf16 v[18:33], v[142:145], v[198:201], v[18:33]
	v_mfma_f32_32x32x16_bf16 v[66:81], v[138:141], v[198:201], v[66:81]
	ds_read_b128 v[198:201], v0 offset:9312
	s_waitcnt lgkmcnt(7)
	v_mfma_f32_32x32x16_bf16 v[2:17], v[142:145], v[202:205], v[2:17]
	v_mfma_f32_32x32x16_bf16 v[34:49], v[138:141], v[202:205], v[34:49]
	ds_read_b128 v[202:205], v0 offset:13920
	v_lshl_add_u64 v[142:143], v[188:189], 0, s[90:91]
	global_load_dwordx4 v[142:145], v[142:143], off offset:2048
	v_lshl_add_u64 v[138:139], v[186:187], 0, s[90:91]
	global_load_dwordx4 v[138:141], v[138:139], off offset:2048
	s_waitcnt lgkmcnt(3)
	v_mfma_f32_32x32x16_bf16 v[82:97], v[130:133], v[190:193], v[82:97]
	v_mfma_f32_32x32x16_bf16 v[114:129], v[134:137], v[190:193], v[114:129]
	s_waitcnt lgkmcnt(2)
	v_mfma_f32_32x32x16_bf16 v[50:65], v[130:133], v[194:197], v[50:65]
	v_mfma_f32_32x32x16_bf16 v[98:113], v[134:137], v[194:197], v[98:113]
	s_waitcnt lgkmcnt(1)
	v_mfma_f32_32x32x16_bf16 v[18:33], v[130:133], v[198:201], v[18:33]
	v_mfma_f32_32x32x16_bf16 v[66:81], v[134:137], v[198:201], v[66:81]
	s_waitcnt lgkmcnt(0)
	v_mfma_f32_32x32x16_bf16 v[2:17], v[130:133], v[202:205], v[2:17]
	v_mfma_f32_32x32x16_bf16 v[34:49], v[134:137], v[202:205], v[34:49]
	v_lshl_add_u64 v[130:131], v[188:189], 0, s[90:91]
	global_load_dwordx4 v[130:133], v[130:131], off offset:3072
	v_lshl_add_u64 v[134:135], v[186:187], 0, s[90:91]
	global_load_dwordx4 v[134:137], v[134:135], off offset:3072
	s_waitcnt vmcnt(12)
	ds_write_b128 v171, v[222:225] offset:18432
	ds_write_b128 v171, v[226:229] offset:23040
	ds_write_b128 v171, v[230:233] offset:27648
	ds_write_b128 v171, v[246:249] offset:32256
	s_add_u32 s18, s10, s36
	s_addc_u32 s19, s11, 0
	v_lshl_add_u64 v[222:223], s[18:19], 0, v[176:177]
	v_lshl_add_u64 v[226:227], s[18:19], 0, v[178:179]
	v_lshl_add_u64 v[230:231], s[18:19], 0, v[180:181]
	v_lshl_add_u64 v[246:247], s[18:19], 0, v[182:183]
	global_load_dwordx4 v[222:225], v[222:223], off
	global_load_dwordx4 v[226:229], v[226:227], off
	global_load_dwordx4 v[230:233], v[230:231], off
	global_load_dwordx4 v[246:249], v[246:247], off
	s_cmp_lg_u32 s6, 16
	s_waitcnt lgkmcnt(0)
	s_barrier
; #define SW_FOR_TOK(j) _Pragma("unroll") for (int j = 0; j < 4; j++)
; #define SW_FOR_FEAT(i, rq) _Pragma("unroll") for (int i = 0; i < 2; i++) _Pragma("unroll") for (int rq = 0; rq < 4; rq++)
; DI void ph_out(const Params& P, int layer, bf16_t* smem) {
;     ...
;     SW_FOR_TOK(j) {
;       const int tl = wn * 128 + j * 32 + l32; const size_t tg = (size_t)m0 + tl;
;       float sq = 0.f;
;       SW_FOR_FEAT(i, rq) {
;         const int c = n0 + wm * 64 + i * 32 + 8 * rq + 4 * h;
;         const float a0 = SWV(i, j, 4 * rq), a1 = SWV(i, j, 4 * rq + 1), a2 = SWV(i, j, 4 * rq + 2), a3 = SWV(i, j, 4 * rq + 3);
;         sq += a0 * a0 + a1 * a1 + a2 * a2 + a3 * a3; (void)c;
;       }
;       sq += __shfl_xor(sq, 32);
;       if (h == 0) ss[tg * 16 + nt * 2 + wm] = sq;
;     }
	s_cbranch_scc1 .LBB0_30
	s_waitcnt vmcnt(0)
	s_waitcnt vmcnt(0)
	v_mul_f32_e32 v130, v115, v115
	v_mul_f32_e32 v131, v119, v119
	v_fmac_f32_e32 v130, v114, v114
	v_fmac_f32_e32 v131, v118, v118
	v_fmac_f32_e32 v130, v116, v116
	v_fmac_f32_e32 v131, v120, v120
	v_fmac_f32_e32 v130, v117, v117
	v_fmac_f32_e32 v131, v121, v121
	v_add_f32_e32 v130, v130, v131
	v_mul_f32_e32 v131, v123, v123
	v_fmac_f32_e32 v131, v122, v122
	v_fmac_f32_e32 v131, v124, v124
	v_fmac_f32_e32 v131, v125, v125
	v_add_f32_e32 v130, v131, v130
	v_mul_f32_e32 v131, v127, v127
	v_fmac_f32_e32 v131, v126, v126
	v_fmac_f32_e32 v131, v128, v128
	v_fmac_f32_e32 v131, v129, v129
	v_add_f32_e32 v130, v131, v130
	v_mul_f32_e32 v131, v83, v83
	v_fmac_f32_e32 v131, v82, v82
	v_fmac_f32_e32 v131, v84, v84
	v_fmac_f32_e32 v131, v85, v85
	v_add_f32_e32 v130, v130, v131
	v_mul_f32_e32 v131, v87, v87
	v_fmac_f32_e32 v131, v86, v86
	v_fmac_f32_e32 v131, v88, v88
	v_fmac_f32_e32 v131, v89, v89
	v_add_f32_e32 v130, v131, v130
	v_mul_f32_e32 v131, v91, v91
	v_fmac_f32_e32 v131, v90, v90
	v_fmac_f32_e32 v131, v92, v92
	v_fmac_f32_e32 v131, v93, v93
	v_add_f32_e32 v130, v131, v130
	v_mul_f32_e32 v131, v95, v95
	v_fmac_f32_e32 v131, v94, v94
	v_cmp_lt_i32_e64 s[6:7], v236, v237
	v_fmac_f32_e32 v131, v96, v96
	v_fmac_f32_e32 v131, v97, v97
	v_cndmask_b32_e64 v0, v238, v236, s[6:7]
	v_lshlrev_b32_e32 v0, 2, v0
	v_add_f32_e32 v132, v131, v130
	ds_bpermute_b32 v133, v0, v132
	s_lshl_b32 s6, s16, 1
	s_lshl_b32 s8, s17, 8
	s_ashr_i32 s7, s6, 31
	s_ashr_i32 s9, s8, 31
	v_lshl_add_u64 v[130:131], s[6:7], 2, v[164:165]
	s_and_saveexec_b64 s[6:7], vcc
	s_cbranch_execz .LBB0_33
	s_waitcnt lgkmcnt(0)
	v_add_f32_e32 v134, v132, v133
	v_mov_b32_e32 v133, s9
	v_or_b32_e32 v132, s8, v162
	v_lshlrev_b64 v[132:133], 6, v[132:133]
	v_lshl_add_u64 v[132:133], v[130:131], 0, v[132:133]
	global_store_dword v[132:133], v134, off

; #define A256_LOADH(kt_, hf_) { a0 = la.ld1(kt_, (hf_) * 4 + 0, tid); a1 = la.ld1(kt_, (hf_) * 4 + 1, tid); a2 = la.ld1(kt_, (hf_) * 4 + 2, tid); a3 = la.ld1(kt_, (hf_) * 4 + 3, tid); }
; #define ZERO_ACC8(a) { _Pragma("unroll") for (int i_ = 0; i_ < 8; i_++) _Pragma("unroll") for (int r_ = 0; r_ < 16; r_++) a[i_][r_] = 0.f; }
; template <bool swap, class LA>
; DI void gemm256_ws(const LA& la, const bf16_t* Wt, const int KS, const int nk, bf16_t* smem, f32x16 (&acc)[8]) {
;     ...
;   A256_LOADH(0, 0) A256_STH(smem, 0)
;   A256_LOADH(0, 1) A256_STH(smem, 1)
;   W256_LD(0, 0, w00, w10) W256_LD(0, 1, w01, w11) W256_LD(0, 2, w02, w12) W256_LD(0, 3, w03, w13)
;   __syncthreads();
;   const int aoff = (tbk * 128 + l32) * LDT + h * 8;
; DI void ph_out(const Params& P, int layer, bf16_t* smem) {
;     ...
;   for (int it = 0;; it++) {
;     int mt, nt; if (!tile_sched256(bid, it, 8, 8, mt, nt)) break;
;     const int m0 = mt * 256, n0 = nt * 128;
;     __syncthreads();
;     f32x16 acc[8]; ZERO_ACC8(acc)
;     LoadTile256 la{cat + (size_t)(2 * mt) * 16 * 8192, 16 * 8192};
;     gemm256_ws<true>(la, W + (size_t)n0 * 1024, 64, 16, smem, acc);
.LBB0_267:
	s_ashr_i32 s3, s2, 31
	s_lshr_b32 s3, s3, 24
	s_add_i32 s3, s2, s3
	s_ashr_i32 s6, s3, 8
	s_and_b32 s3, s3, 0xffffff00
	s_sub_i32 s2, s2, s3
	s_ashr_i32 s3, s2, 31
	s_lshr_b32 s3, s3, 29
	s_add_i32 s3, s2, s3
	s_ashr_i32 s17, s3, 3
	s_sub_i32 s3, s6, s17
	s_add_i32 s17, s17, s14
	s_lshl_b32 s16, s3, 3
	s_lshl_b32 s6, s17, 1
	s_add_i32 s16, s16, s2
	s_ashr_i32 s7, s6, 31
	s_lshl_b32 s2, s16, 7
	s_lshl_b64 s[6:7], s[6:7], 18
	v_mov_b32_e32 v0, v234
	s_barrier
	s_add_u32 s8, s84, s6
	s_addc_u32 s9, s85, s7
	v_lshlrev_b32_e32 v2, 3, v0
	s_ashr_i32 s3, s2, 31
	v_add_u32_e32 v6, 0x800, v2
	s_lshl_b64 s[6:7], s[2:3], 11
	v_readlane_b32 s10, v253, 53
	v_ashrrev_i32_e32 v3, 31, v2
	v_ashrrev_i32_e32 v7, 31, v6
	v_readlane_b32 s11, v253, 54
	s_add_u32 s6, s10, s6
	v_lshlrev_b64 v[176:177], 1, v[2:3]
	v_lshlrev_b64 v[178:179], 1, v[6:7]
	v_add_u32_e32 v6, 0x1000, v2
	v_add_u32_e32 v2, 0x1800, v2
	s_addc_u32 s7, s11, s7
	v_ashrrev_i32_e32 v7, 31, v6
	v_ashrrev_i32_e32 v3, 31, v2
	v_lshlrev_b64 v[180:181], 1, v[6:7]
	v_lshlrev_b64 v[182:183], 1, v[2:3]
	s_add_u32 s10, s8, 0x40000
	v_lshl_add_u64 v[4:5], s[8:9], 0, v[176:177]
	v_lshl_add_u64 v[8:9], s[8:9], 0, v[178:179]
	v_lshl_add_u64 v[12:13], s[8:9], 0, v[180:181]
	v_lshl_add_u64 v[2:3], s[8:9], 0, v[182:183]
	s_addc_u32 s11, s9, 0
	v_ashrrev_i32_e32 v36, 6, v0
	global_load_dwordx4 v[4:7], v[4:5], off
	s_nop 0
	global_load_dwordx4 v[8:11], v[8:9], off
	s_nop 0
	global_load_dwordx4 v[12:15], v[12:13], off
	s_nop 0
	global_load_dwordx4 v[16:19], v[2:3], off
	v_lshl_add_u64 v[2:3], s[10:11], 0, v[176:177]
	v_lshl_add_u64 v[24:25], s[10:11], 0, v[178:179]
	v_lshl_add_u64 v[28:29], s[10:11], 0, v[180:181]
	v_lshl_add_u64 v[32:33], s[10:11], 0, v[182:183]
	v_lshlrev_b32_e32 v37, 4, v0
	v_and_b32_e32 v36, -2, v36
	global_load_dwordx4 v[20:23], v[2:3], off
	s_nop 0
	global_load_dwordx4 v[24:27], v[24:25], off
	s_nop 0
	global_load_dwordx4 v[28:31], v[28:29], off
	s_nop 0
	global_load_dwordx4 v[32:35], v[32:33], off
	v_and_b32_e32 v3, 31, v0
	v_lshrrev_b32_e32 v39, 3, v0
	v_lshlrev_b32_e32 v40, 1, v0
	v_lshrrev_b32_e32 v41, 1, v0
	v_and_b32_e32 v0, 0x3f0, v37
	v_and_b32_e32 v38, 0x70, v37
	v_ashrrev_i32_e32 v37, 31, v36
	v_lshlrev_b64 v[36:37], 16, v[36:37]
	v_lshl_add_u64 v[36:37], s[6:7], 0, v[36:37]
	v_lshl_add_u64 v[186:187], v[36:37], 0, v[0:1]
	s_mov_b64 s[6:7], 0x10000
	v_lshl_add_u64 v[188:189], v[186:187], 0, s[6:7]
	v_add_co_u32_e64 v36, s[6:7], s94, v186
	s_movk_i32 s18, 0x80
	s_nop 0
	v_addc_co_u32_e64 v37, s[6:7], 0, v187, s[6:7]
	global_load_dwordx4 v[154:157], v[36:37], off
	global_load_dwordx4 v[158:161], v[186:187], off
	global_load_dwordx4 v[146:149], v[36:37], off offset:1024
	global_load_dwordx4 v[150:153], v[186:187], off offset:1024
	global_load_dwordx4 v[142:145], v[36:37], off offset:2048
	global_load_dwordx4 v[138:141], v[186:187], off offset:2048
	global_load_dwordx4 v[130:133], v[36:37], off offset:3072
	global_load_dwordx4 v[134:137], v[186:187], off offset:3072
	v_mov_b32_e32 v2, 0
	v_and_or_b32 v3, v40, s18, v3
	v_and_b32_e32 v40, 16, v41
	v_mad_u64_u32 v[184:185], s[18:19], v39, s0, v[38:39]
	v_mad_u32_u24 v169, v3, s0, v40
	s_mov_b32 s6, 0
	v_mov_b32_e32 v3, v2
	v_mov_b32_e32 v50, v2
	v_mov_b32_e32 v51, v2
	v_mov_b32_e32 v52, v2
	v_mov_b32_e32 v53, v2
	v_mov_b32_e32 v54, v2
	v_mov_b32_e32 v55, v2
	v_mov_b32_e32 v56, v2
	v_mov_b32_e32 v57, v2
	v_mov_b32_e32 v58, v2
	v_mov_b32_e32 v59, v2
	v_mov_b32_e32 v60, v2
	v_mov_b32_e32 v61, v2
	v_mov_b32_e32 v62, v2
	v_mov_b32_e32 v63, v2
	v_mov_b32_e32 v64, v2
	v_mov_b32_e32 v65, v2
	v_mov_b32_e32 v82, v2
	s_waitcnt vmcnt(15)
	ds_write_b128 v184, v[4:7]
	s_waitcnt vmcnt(14)
	ds_write_b128 v184, v[8:11] offset:4608
	s_waitcnt vmcnt(13)
	ds_write_b128 v184, v[12:15] offset:9216
	s_waitcnt vmcnt(12)
	ds_write_b128 v184, v[16:19] offset:13824
	s_waitcnt vmcnt(11)
	ds_write_b128 v184, v[20:23] offset:18432
	s_waitcnt vmcnt(10)
	ds_write_b128 v184, v[24:27] offset:23040
	s_waitcnt vmcnt(9)
	ds_write_b128 v184, v[28:31] offset:27648
	s_waitcnt vmcnt(8)
	ds_write_b128 v184, v[32:35] offset:32256
	v_mov_b32_e32 v4, v2
	v_mov_b32_e32 v5, v2
	v_mov_b32_e32 v6, v2
	v_mov_b32_e32 v7, v2
	v_mov_b32_e32 v8, v2
	v_mov_b32_e32 v9, v2
	v_mov_b32_e32 v10, v2
	v_mov_b32_e32 v11, v2
	v_mov_b32_e32 v12, v2
	v_mov_b32_e32 v13, v2
	v_mov_b32_e32 v14, v2
	v_mov_b32_e32 v15, v2
	v_mov_b32_e32 v16, v2
	v_mov_b32_e32 v17, v2
	v_mov_b32_e32 v18, v2
	v_mov_b32_e32 v19, v2
	v_mov_b32_e32 v20, v2
	v_mov_b32_e32 v21, v2
	v_mov_b32_e32 v22, v2
	v_mov_b32_e32 v23, v2
	v_mov_b32_e32 v24, v2
	v_mov_b32_e32 v25, v2
	v_mov_b32_e32 v26, v2
	v_mov_b32_e32 v27, v2
	v_mov_b32_e32 v28, v2
	v_mov_b32_e32 v29, v2
	v_mov_b32_e32 v30, v2
	v_mov_b32_e32 v31, v2
	v_mov_b32_e32 v32, v2
	v_mov_b32_e32 v33, v2
	v_mov_b32_e32 v83, v2
	v_mov_b32_e32 v84, v2
	v_mov_b32_e32 v85, v2
	v_mov_b32_e32 v86, v2
	v_mov_b32_e32 v87, v2
	v_mov_b32_e32 v88, v2
	v_mov_b32_e32 v89, v2
	v_mov_b32_e32 v90, v2
	v_mov_b32_e32 v91, v2
	v_mov_b32_e32 v92, v2
	v_mov_b32_e32 v93, v2
	v_mov_b32_e32 v94, v2
	v_mov_b32_e32 v95, v2
	v_mov_b32_e32 v96, v2
	v_mov_b32_e32 v97, v2
	v_mov_b32_e32 v34, v2
	v_mov_b32_e32 v35, v2
	v_mov_b32_e32 v36, v2
	v_mov_b32_e32 v37, v2
	v_mov_b32_e32 v38, v2
	v_mov_b32_e32 v39, v2
	v_mov_b32_e32 v40, v2
	v_mov_b32_e32 v41, v2
	v_mov_b32_e32 v42, v2
	v_mov_b32_e32 v43, v2
	v_mov_b32_e32 v44, v2
	v_mov_b32_e32 v45, v2
	v_mov_b32_e32 v46, v2
	v_mov_b32_e32 v47, v2
	v_mov_b32_e32 v48, v2
	v_mov_b32_e32 v49, v2
	v_mov_b32_e32 v66, v2
	v_mov_b32_e32 v67, v2
	v_mov_b32_e32 v68, v2
	v_mov_b32_e32 v69, v2
	v_mov_b32_e32 v70, v2
	v_mov_b32_e32 v71, v2
	v_mov_b32_e32 v72, v2
	v_mov_b32_e32 v73, v2
	v_mov_b32_e32 v74, v2
	v_mov_b32_e32 v75, v2
	v_mov_b32_e32 v76, v2
	v_mov_b32_e32 v77, v2
	v_mov_b32_e32 v78, v2
	v_mov_b32_e32 v79, v2
	v_mov_b32_e32 v80, v2
	v_mov_b32_e32 v81, v2
	v_mov_b32_e32 v98, v2
	v_mov_b32_e32 v99, v2
	v_mov_b32_e32 v100, v2
	v_mov_b32_e32 v101, v2
	v_mov_b32_e32 v102, v2
	v_mov_b32_e32 v103, v2
	v_mov_b32_e32 v104, v2
	v_mov_b32_e32 v105, v2
	v_mov_b32_e32 v106, v2
	v_mov_b32_e32 v107, v2
	v_mov_b32_e32 v108, v2
	v_mov_b32_e32 v109, v2
	v_mov_b32_e32 v110, v2
	v_mov_b32_e32 v111, v2
	v_mov_b32_e32 v112, v2
	v_mov_b32_e32 v113, v2
	v_mov_b32_e32 v114, v2
	v_mov_b32_e32 v115, v2
	v_mov_b32_e32 v116, v2
	v_mov_b32_e32 v117, v2
	v_mov_b32_e32 v118, v2
	v_mov_b32_e32 v119, v2
	v_mov_b32_e32 v120, v2
	v_mov_b32_e32 v121, v2
	v_mov_b32_e32 v122, v2
	v_mov_b32_e32 v123, v2
	v_mov_b32_e32 v124, v2
	v_mov_b32_e32 v125, v2
	v_mov_b32_e32 v126, v2
	v_mov_b32_e32 v127, v2
	v_mov_b32_e32 v128, v2
	v_mov_b32_e32 v129, v2
	s_waitcnt lgkmcnt(0)
	s_barrier
; #define A256_LOADH(kt_, hf_) { a0 = la.ld1(kt_, (hf_) * 4 + 0, tid); a1 = la.ld1(kt_, (hf_) * 4 + 1, tid); a2 = la.ld1(kt_, (hf_) * 4 + 2, tid); a3 = la.ld1(kt_, (hf_) * 4 + 3, tid); }
; template <bool swap, class LA>
; DI void gemm256_ws(const LA& la, const bf16_t* Wt, const int KS, const int nk, bf16_t* smem, f32x16 (&acc)[8]) {
;     ...
;   for (int kt = 0; kt < nk; kt++) {
;     const int cur = kt & 1; const int kn = (kt + 1 < nk) ? kt + 1 : last;
;     const bf16_t* sp = smem + cur * ATILE_E + aoff;
;     bf16_t* nxt = smem + (cur ^ 1) * ATILE_E;
;     A256_LOADH(kn, 0)
;     MMA256(0, w00, w10) W256_LD(kn, 0, w00, w10)
;     MMA256(1, w01, w11) W256_LD(kn, 1, w01, w11)
;     A256_STH(nxt, 0)
;     A256_LOADH(kn, 1)
;     MMA256(2, w02, w12) W256_LD(kn, 2, w02, w12)
;     MMA256(3, w03, w13) W256_LD(kn, 3, w03, w13)
;     A256_STH(nxt, 1)
;     __syncthreads();
	s_lshl_b32 s36, 1, 14
	s_add_u32 s18, s8, s36
	s_addc_u32 s19, s9, 0
	v_lshl_add_u64 v[206:207], s[18:19], 0, v[176:177]
	v_lshl_add_u64 v[210:211], s[18:19], 0, v[178:179]
	v_lshl_add_u64 v[214:215], s[18:19], 0, v[180:181]
	v_lshl_add_u64 v[218:219], s[18:19], 0, v[182:183]
	global_load_dwordx4 v[206:209], v[206:207], off
	global_load_dwordx4 v[210:213], v[210:211], off
	global_load_dwordx4 v[214:217], v[214:215], off
	global_load_dwordx4 v[218:221], v[218:219], off
	s_add_u32 s18, s10, s36
	s_addc_u32 s19, s11, 0
	v_lshl_add_u64 v[222:223], s[18:19], 0, v[176:177]
	v_lshl_add_u64 v[226:227], s[18:19], 0, v[178:179]
	v_lshl_add_u64 v[230:231], s[18:19], 0, v[180:181]
	v_lshl_add_u64 v[246:247], s[18:19], 0, v[182:183]
	global_load_dwordx4 v[222:225], v[222:223], off
	global_load_dwordx4 v[226:229], v[226:227], off
	global_load_dwordx4 v[230:233], v[230:231], off
	global_load_dwordx4 v[246:249], v[246:247], off
